# grid barrier: the first workgroup to arrive on each XCD issues an early buffer_wbl2 so the XCD leader's release writeback has less left to flush
# baseline (speedup 1.0000x reference)
; __device__ __forceinline__ unsigned xb_ld(unsigned* p)              { return __hip_atomic_load(p, __ATOMIC_RELAXED, __HIP_MEMORY_SCOPE_AGENT); }
; __device__ __forceinline__ unsigned xb_add(unsigned* p, unsigned v) { return __hip_atomic_fetch_add(p, v, __ATOMIC_RELAXED, __HIP_MEMORY_SCOPE_AGENT); }
; #define XB_SPIN(cond, bar) do { unsigned _sp = 0; while (cond) { __builtin_amdgcn_s_sleep(1); \
;     if ((++_sp & 255u) == 0u) { if (xb_ld(&(bar)[XB_TMO])) break; if (_sp > XB_SPIN_CAP) { atomicAdd(&(bar)[XB_TMO], 1u); break; } } } } while (0)
; __device__ __forceinline__ void xcd_barrier(const XcdBarrier& b) {
;     ...
;         const unsigned old = xb_add(&bar[XB_XSUB(b.x)], 1u);
;         const unsigned gen = old / nloc;
;         if (old + 1u == (gen + 1u) * nloc) {
;             __builtin_amdgcn_fence(__ATOMIC_RELEASE, "agent");
;             asm volatile("s_waitcnt vmcnt(0)" ::: "memory");
;             const unsigned og = xb_add(&bar[XB_TOP], 1u);
;             const unsigned tg = og / nx;
;             if (og + 1u == (tg + 1u) * nx) xb_add(&bar[XB_TOPGEN], 1u);
;             else XB_SPIN(xb_ld(&bar[XB_TOPGEN]) == tg, bar);
;             __builtin_amdgcn_fence(__ATOMIC_ACQUIRE, "agent");
;             xb_add(&bar[XB_XGEN(b.x)], 1u);
;             asm volatile("s_waitcnt vmcnt(0)" ::: "memory");
;         } else {
;             XB_SPIN(xb_ld(&bar[XB_XGEN(b.x)]) == gen, bar);
.LBB0_439:
	global_atomic_add v4, v[152:153], v192, off sc0
	v_cvt_f32_u32_e32 v0, v3
	v_sub_u32_e32 v5, 0, v3
	v_rcp_iflag_f32_e32 v0, v0
	s_nop 0
	v_mul_f32_e32 v0, 0x4f7ffffe, v0
	v_cvt_u32_f32_e32 v0, v0
	v_mul_lo_u32 v5, v5, v0
	v_mul_hi_u32 v5, v0, v5
	v_add_u32_e32 v0, v0, v5
	s_waitcnt vmcnt(0)
	v_mul_hi_u32 v0, v4, v0
	v_mul_lo_u32 v5, v0, v3
	v_sub_u32_e32 v5, v4, v5
	v_add_u32_e32 v6, 1, v0
	v_cmp_ge_u32_e32 vcc, v5, v3
	v_add_u32_e32 v4, 1, v4
	s_nop 0
	v_cndmask_b32_e32 v0, v0, v6, vcc
	v_sub_u32_e32 v6, v5, v3
	v_cndmask_b32_e32 v5, v5, v6, vcc
	v_add_u32_e32 v6, 1, v0
	v_cmp_ge_u32_e32 vcc, v5, v3
	s_nop 1
	v_cndmask_b32_e32 v0, v0, v6, vcc
	v_mul_lo_u32 v5, v3, v0
	v_add_u32_e32 v3, v5, v3
	v_cmp_ne_u32_e32 vcc, v4, v3
	s_and_saveexec_b64 s[4:5], vcc
	s_xor_b64 s[4:5], exec, s[4:5]
	s_cbranch_execz .LBB0_453
	v_add_u32_e32 v6, 1, v5
	v_cmp_eq_u32_e32 vcc, v4, v6
	s_cbranch_vccz .Lwb_first_skip
	buffer_wbl2 sc1
.Lwb_first_skip:
	s_waitcnt lgkmcnt(0)
	global_load_dword v2, v[154:155], off sc1
	s_waitcnt vmcnt(0)
	v_cmp_eq_u32_e32 vcc, v2, v0
	s_and_saveexec_b64 s[6:7], vcc
	s_cbranch_execz .LBB0_452
	s_mov_b32 s20, 1
	s_mov_b64 s[8:9], 0
	s_branch .LBB0_443
